# K-prep hook: trailing s_waitcnt vmcnt(0) after the fix-up stores dropped (later counted waits already cover them); plus the mixer-B combine bf16 pack via v_cvt_pk_bf16_f32
# speedup vs baseline: 1.0091x; 1.0091x over previous
; #define PG8_BAR __builtin_amdgcn_s_barrier()
; template <class Epi, class Sched, bool ALIGN_EPI = false, bool SP2 = false>
; __device__ __forceinline__ void gemm_phase(PG8_LAS unsigned char* lds, const Gemm g, const Sched& S, const Epi& E) {
;     ...
;         if constexpr (ALIGN_EPI) { if (wr == 0) PG8_BAR; }
;         if constexpr (!Epi::AFTER_DRAIN) { E(acc, cur, wr, wc, fr, fq, rsv); S.done(cur); }
;         if (!has_next) break;
; #pragma unroll
;         for (int a = 0; a < 2; ++a)
; #pragma unroll
;             for (int b = 0; b < 2; ++b)
; #pragma unroll
;                 for (int m = 0; m < 4; ++m)
; #pragma unroll
;                     for (int n = 0; n < 2; ++n) acc[a][b][m][n] = (f32x4){0.f, 0.f, 0.f, 0.f};
;         cur = nxt; cA = nA; cB = nB; ++ui;
;         if constexpr (ALIGN_EPI) { if (wr == 1) PG8_BAR; }
;     __device__ __forceinline__ void done(const pg8::Unit& u) const {
;     ...
;         asm volatile("s_waitcnt vmcnt(0)" ::: "memory");
;     }
.LBB0_220:
.LBB0_221:
	s_andn2_b64 vcc, exec, s[4:5]
	s_mov_b64 s[4:5], -1
	s_cbranch_vccnz .LBB0_117
	s_andn2_b64 vcc, exec, s[76:77]
	s_cbranch_vccnz .LBB0_116
	s_barrier
	s_branch .LBB0_116
